# attention phase: all windowed-attention units go through the dynamic work queue (nstat 6G -> 0) so workgroups that pick up a fifth diff-attention unit carry no static windowed units; on top of v42
# speedup vs baseline: 1.0038x; 1.0005x over previous
; DI void phase_attn(const Cx& a, LAS unsigned char* lds, int l) {
;     ...
;     const int nstat = 6 * a.G;
;     for (int w = a.vcu; w < nstat && w < 2048; w += a.G) wa_unit(a, lds, l, w >> 7, (w >> 6) & 1, w & 63);
;     const int nDAc = lastl ? 0 : 64, nWL = (2048 > nstat) ? 2048 - nstat : 0, nWS = lastl ? 0 : 128, total = nDAc + nWL + nWS;
.LBB0_433:
	s_mul_i32 s49, s47, 0
	s_min_i32 s7, s49, 0x800
	s_cmp_ge_i32 s72, s7
	s_cbranch_scc1 .LBB0_455
	s_lshl_b32 s12, s50, 3
	s_add_u32 s0, s74, 0xc200000
	s_addc_u32 s1, s75, 0
	s_mov_b32 s13, s72
	s_branch .LBB0_436
